# mixer-1: first group of 8x8 bf16 register transposes uses DPP moves (lane^4/^2/^1) instead of LDS shuffles
# baseline (speedup 1.0000x reference)
; DI unsigned pk2(float lo, float hi) { f32x2 v = {lo, hi}; bf16x2_t b = __builtin_convertvector(v, bf16x2_t); return __builtin_bit_cast(unsigned, b); }
; DI u32x4 tr8x8(u32x4 w, int lane) {
;     { const bool b = (lane & 4) != 0;
;       const unsigned s0 = b ? w.x : w.z, s1 = b ? w.y : w.w, r0 = __shfl_xor(s0, 4), r1 = __shfl_xor(s1, 4);
;       if (b) { w.x = r0; w.y = r1; } else { w.z = r0; w.w = r1; } }
;     { const bool b = (lane & 2) != 0;
;       const unsigned s0 = b ? w.x : w.y, s1 = b ? w.z : w.w, r0 = __shfl_xor(s0, 2), r1 = __shfl_xor(s1, 2);
;       if (b) { w.x = r0; w.z = r1; } else { w.y = r0; w.w = r1; } }
;     { const bool b = (lane & 1) != 0;
;       const unsigned p0 = __shfl_xor(w.x, 1), p1 = __shfl_xor(w.y, 1), p2 = __shfl_xor(w.z, 1), p3 = __shfl_xor(w.w, 1);
;       if (b) { w.x = (p0 >> 16) | (w.x & 0xffff0000u); w.y = (p1 >> 16) | (w.y & 0xffff0000u); w.z = (p2 >> 16) | (w.z & 0xffff0000u); w.w = (p3 >> 16) | (w.w & 0xffff0000u); }
;       else   { w.x = (w.x & 0xffffu) | (p0 << 16); w.y = (w.y & 0xffffu) | (p1 << 16); w.z = (w.z & 0xffffu) | (p2 << 16); w.w = (w.w & 0xffffu) | (p3 << 16); } }
;     DI void operator()(const f32x4 (&acc)[2][2][4][2], const Unit& u, int wr, int wc, int fr, int fq) const {
;     ...
;                     for (int bj = 0; bj < 2; ++bj) {
;                         const f32x4 x0 = acc[ai][bj][m][0], x1 = acc[ai][bj][m][1];
;                         *(f32x4*)(o + 32 * bj) = x0; *(f32x4*)(o + 32 * bj + 4) = x1;
;                         u32x4 w; w.x = pk2(x0[0], x0[1]); w.y = pk2(x0[2], x0[3]); w.z = pk2(x1[0], x1[1]); w.w = pk2(x1[2], x1[3]);
;                         *(u32x4*)(t + 32 * bj * 8) = tr8x8(w, fr);
.LBB0_147:
	s_andn2_b64 vcc, exec, s[6:7]
	s_cbranch_vccnz .LBB0_213
	v_and_b32_e32 v130, 64, v200
	v_xor_b32_e32 v129, 4, v200
	v_add_u32_e32 v130, 64, v130
	v_and_b32_e32 v128, 4, v174
	v_cmp_lt_i32_e32 vcc, v129, v130
	v_cvt_pk_bf16_f32 v132, v124, v125
	v_cvt_pk_bf16_f32 v133, v126, v127
	v_cndmask_b32_e32 v129, v200, v129, vcc
	v_cvt_pk_bf16_f32 v134, v120, v121
	v_cvt_pk_bf16_f32 v135, v122, v123
	v_cmp_eq_u32_e64 s[8:9], 0, v128
	v_lshlrev_b32_e32 v141, 2, v129
	v_xor_b32_e32 v131, 2, v200
	v_cndmask_b32_e64 v128, v132, v134, s[8:9]
	v_cndmask_b32_e64 v137, v133, v135, s[8:9]
	s_nop 1
	v_mov_b32_dpp v128, v128 row_half_mirror row_mask:0xf bank_mask:0xf
	s_nop 1
	v_mov_b32_dpp v128, v128 quad_perm:[3,2,1,0] row_mask:0xf bank_mask:0xf
	s_nop 1
	v_mov_b32_dpp v137, v137 row_half_mirror row_mask:0xf bank_mask:0xf
	s_nop 1
	v_mov_b32_dpp v137, v137 quad_perm:[3,2,1,0] row_mask:0xf bank_mask:0xf
	v_and_b32_e32 v129, 2, v174
	v_cmp_lt_i32_e32 vcc, v131, v130
	v_cmp_eq_u32_e64 s[6:7], 0, v129
	s_waitcnt lgkmcnt(0)
	v_cndmask_b32_e64 v134, v134, v128, s[8:9]
	v_cndmask_b32_e32 v131, v200, v131, vcc
	v_cndmask_b32_e64 v135, v135, v137, s[8:9]
	v_cndmask_b32_e64 v138, v137, v133, s[8:9]
	v_cndmask_b32_e64 v128, v128, v132, s[8:9]
	v_lshlrev_b32_e32 v140, 2, v131
	v_cndmask_b32_e64 v129, v128, v138, s[6:7]
	v_cndmask_b32_e64 v132, v134, v135, s[6:7]
	s_nop 1
	v_mov_b32_dpp v133, v132 quad_perm:[2,3,0,1] row_mask:0xf bank_mask:0xf
	s_nop 1
	v_mov_b32_dpp v129, v129 quad_perm:[2,3,0,1] row_mask:0xf bank_mask:0xf
	v_xor_b32_e32 v131, 1, v200
	v_cmp_lt_i32_e32 vcc, v131, v130
	s_waitcnt lgkmcnt(0)
	v_cndmask_b32_e64 v132, v135, v133, s[6:7]
	v_cndmask_b32_e32 v130, v200, v131, vcc
	v_lshlrev_b32_e32 v137, 2, v130
	v_cndmask_b32_e64 v133, v133, v134, s[6:7]
	v_cndmask_b32_e64 v134, v138, v129, s[6:7]
	v_cndmask_b32_e64 v138, v129, v128, s[6:7]
	s_nop 1
	v_mov_b32_dpp v143, v138 quad_perm:[1,0,3,2] row_mask:0xf bank_mask:0xf
	s_nop 1
	v_mov_b32_dpp v142, v134 quad_perm:[1,0,3,2] row_mask:0xf bank_mask:0xf
	s_nop 1
	v_mov_b32_dpp v139, v133 quad_perm:[1,0,3,2] row_mask:0xf bank_mask:0xf
	s_nop 1
	v_mov_b32_dpp v135, v132 quad_perm:[1,0,3,2] row_mask:0xf bank_mask:0xf
	v_and_b32_e32 v128, 1, v174
	v_cmp_eq_u32_e32 vcc, 1, v128
	s_and_saveexec_b64 s[10:11], vcc
	s_xor_b64 s[10:11], exec, s[10:11]
	s_cbranch_execz .LBB0_150
	s_waitcnt lgkmcnt(0)
	v_lshrrev_b32_e32 v128, 16, v143
	v_lshrrev_b32_e32 v129, 16, v142
	v_lshrrev_b32_e32 v130, 16, v139
	v_lshrrev_b32_e32 v131, 16, v135
	v_and_or_b32 v128, v138, s21, v128
	v_and_or_b32 v129, v134, s21, v129
	v_and_or_b32 v130, v133, s21, v130
	v_and_or_b32 v131, v132, s21, v131

; DI unsigned pk2(float lo, float hi) { f32x2 v = {lo, hi}; bf16x2_t b = __builtin_convertvector(v, bf16x2_t); return __builtin_bit_cast(unsigned, b); }
; DI u32x4 tr8x8(u32x4 w, int lane) {
;     { const bool b = (lane & 4) != 0;
;       const unsigned s0 = b ? w.x : w.z, s1 = b ? w.y : w.w, r0 = __shfl_xor(s0, 4), r1 = __shfl_xor(s1, 4);
;       if (b) { w.x = r0; w.y = r1; } else { w.z = r0; w.w = r1; } }
;     { const bool b = (lane & 2) != 0;
;       const unsigned s0 = b ? w.x : w.y, s1 = b ? w.z : w.w, r0 = __shfl_xor(s0, 2), r1 = __shfl_xor(s1, 2);
;       if (b) { w.x = r0; w.z = r1; } else { w.y = r0; w.w = r1; } }
;     { const bool b = (lane & 1) != 0;
;       const unsigned p0 = __shfl_xor(w.x, 1), p1 = __shfl_xor(w.y, 1), p2 = __shfl_xor(w.z, 1), p3 = __shfl_xor(w.w, 1);
;       if (b) { w.x = (p0 >> 16) | (w.x & 0xffff0000u); w.y = (p1 >> 16) | (w.y & 0xffff0000u); w.z = (p2 >> 16) | (w.z & 0xffff0000u); w.w = (p3 >> 16) | (w.w & 0xffff0000u); }
;       else   { w.x = (w.x & 0xffffu) | (p0 << 16); w.y = (w.y & 0xffffu) | (p1 << 16); w.z = (w.z & 0xffffu) | (p2 << 16); w.w = (w.w & 0xffffu) | (p3 << 16); } }
;     DI void operator()(const f32x4 (&acc)[2][2][4][2], const Unit& u, int wr, int wc, int fr, int fq) const {
;     ...
;                         bf16_t* t = vt + (((size_t)((row >> 6) * 4 + head) * 8 + ((row >> 3) & 7)) * 128 + f0 + (fr & 7)) * 8;
; #pragma unroll
;                         for (int bj = 0; bj < 2; ++bj) {
;                             const f32x4 x0 = acc[ai][bj][m][0], x1 = acc[ai][bj][m][1];
;                             u32x4 w; w.x = pk2(x0[0], x0[1]); w.y = pk2(x0[2], x0[3]); w.z = pk2(x1[0], x1[1]); w.w = pk2(x1[2], x1[3]);
;                             *(u32x4*)(t + 64 * bj * 8) = tr8x8(w, fr);
.LBB0_152:
	s_or_b64 exec, exec, s[10:11]
	v_ashrrev_i32_e32 v134, 4, v158
	v_and_or_b32 v134, v134, -4, s19
	v_lshlrev_b32_e32 v138, 4, v174
	v_ashrrev_i32_e32 v133, 31, v136
	v_and_or_b32 v132, v174, 7, v136
	s_waitcnt lgkmcnt(0)
	v_ashrrev_i32_e32 v135, 31, v134
	v_and_b32_e32 v160, 0x380, v138
	v_lshl_add_u64 v[138:139], v[132:133], 0, v[160:161]
	v_lshlrev_b64 v[142:143], 14, v[134:135]
	v_lshlrev_b64 v[134:135], 4, v[138:139]
	v_lshl_add_u64 v[138:139], s[46:47], 0, v[142:143]
	v_lshl_add_u64 v[138:139], v[138:139], 0, v[134:135]
	global_store_dwordx4 v[138:139], v[128:131], off
	s_nop 1
	v_cvt_pk_bf16_f32 v128, v116, v117
	v_cvt_pk_bf16_f32 v129, v118, v119
	v_cvt_pk_bf16_f32 v130, v112, v113
	v_cvt_pk_bf16_f32 v131, v114, v115
	v_cndmask_b32_e64 v142, v128, v130, s[8:9]
	v_cndmask_b32_e64 v143, v129, v131, s[8:9]
	s_nop 1
	v_mov_b32_dpp v142, v142 row_half_mirror row_mask:0xf bank_mask:0xf
	s_nop 1
	v_mov_b32_dpp v142, v142 quad_perm:[3,2,1,0] row_mask:0xf bank_mask:0xf
	s_nop 1
	v_mov_b32_dpp v143, v143 row_half_mirror row_mask:0xf bank_mask:0xf
	s_nop 1
	v_mov_b32_dpp v143, v143 quad_perm:[3,2,1,0] row_mask:0xf bank_mask:0xf
	s_waitcnt lgkmcnt(0)
	v_cndmask_b32_e64 v130, v130, v142, s[8:9]
	v_cndmask_b32_e64 v131, v131, v143, s[8:9]
	v_cndmask_b32_e64 v129, v143, v129, s[8:9]
	v_cndmask_b32_e64 v128, v142, v128, s[8:9]
	v_cndmask_b32_e64 v142, v128, v129, s[6:7]
	v_cndmask_b32_e64 v143, v130, v131, s[6:7]
	s_nop 1
	v_mov_b32_dpp v160, v142 quad_perm:[2,3,0,1] row_mask:0xf bank_mask:0xf
	s_nop 1
	v_mov_b32_dpp v143, v143 quad_perm:[2,3,0,1] row_mask:0xf bank_mask:0xf
	s_waitcnt lgkmcnt(0)
	v_cndmask_b32_e64 v159, v129, v160, s[6:7]
	v_cndmask_b32_e64 v142, v131, v143, s[6:7]
	v_cndmask_b32_e64 v143, v143, v130, s[6:7]
	v_cndmask_b32_e64 v175, v160, v128, s[6:7]
	s_nop 1
	v_mov_b32_dpp v178, v175 quad_perm:[1,0,3,2] row_mask:0xf bank_mask:0xf
	s_nop 1
	v_mov_b32_dpp v177, v159 quad_perm:[1,0,3,2] row_mask:0xf bank_mask:0xf
	s_nop 1
	v_mov_b32_dpp v176, v143 quad_perm:[1,0,3,2] row_mask:0xf bank_mask:0xf
	s_nop 1
	v_mov_b32_dpp v160, v142 quad_perm:[1,0,3,2] row_mask:0xf bank_mask:0xf
	s_and_saveexec_b64 s[10:11], vcc
	s_xor_b64 s[10:11], exec, s[10:11]
	s_cbranch_execz .LBB0_154
	s_waitcnt lgkmcnt(0)
	v_lshrrev_b32_e32 v128, 16, v178
	v_lshrrev_b32_e32 v129, 16, v177
	v_lshrrev_b32_e32 v130, 16, v176
	v_lshrrev_b32_e32 v131, 16, v160
	v_and_or_b32 v128, v175, s21, v128
	v_and_or_b32 v129, v159, s21, v129
	v_and_or_b32 v130, v143, s21, v130
	v_and_or_b32 v131, v142, s21, v131

; DI unsigned pk2(float lo, float hi) { f32x2 v = {lo, hi}; bf16x2_t b = __builtin_convertvector(v, bf16x2_t); return __builtin_bit_cast(unsigned, b); }
; DI u32x4 tr8x8(u32x4 w, int lane) {
;     { const bool b = (lane & 4) != 0;
;       const unsigned s0 = b ? w.x : w.z, s1 = b ? w.y : w.w, r0 = __shfl_xor(s0, 4), r1 = __shfl_xor(s1, 4);
;       if (b) { w.x = r0; w.y = r1; } else { w.z = r0; w.w = r1; } }
;     { const bool b = (lane & 2) != 0;
;       const unsigned s0 = b ? w.x : w.y, s1 = b ? w.z : w.w, r0 = __shfl_xor(s0, 2), r1 = __shfl_xor(s1, 2);
;       if (b) { w.x = r0; w.z = r1; } else { w.y = r0; w.w = r1; } }
;     { const bool b = (lane & 1) != 0;
;       const unsigned p0 = __shfl_xor(w.x, 1), p1 = __shfl_xor(w.y, 1), p2 = __shfl_xor(w.z, 1), p3 = __shfl_xor(w.w, 1);
;       if (b) { w.x = (p0 >> 16) | (w.x & 0xffff0000u); w.y = (p1 >> 16) | (w.y & 0xffff0000u); w.z = (p2 >> 16) | (w.z & 0xffff0000u); w.w = (p3 >> 16) | (w.w & 0xffff0000u); }
;       else   { w.x = (w.x & 0xffffu) | (p0 << 16); w.y = (w.y & 0xffffu) | (p1 << 16); w.z = (w.z & 0xffffu) | (p2 << 16); w.w = (w.w & 0xffffu) | (p3 << 16); } }
;     DI void operator()(const f32x4 (&acc)[2][2][4][2], const Unit& u, int wr, int wc, int fr, int fq) const {
;     ...
;                         bf16_t* t = vt + (((size_t)((row >> 6) * 4 + head) * 8 + ((row >> 3) & 7)) * 128 + f0 + (fr & 7)) * 8;
; #pragma unroll
;                         for (int bj = 0; bj < 2; ++bj) {
;                             const f32x4 x0 = acc[ai][bj][m][0], x1 = acc[ai][bj][m][1];
;                             u32x4 w; w.x = pk2(x0[0], x0[1]); w.y = pk2(x0[2], x0[3]); w.z = pk2(x1[0], x1[1]); w.w = pk2(x1[2], x1[3]);
;                             *(u32x4*)(t + 64 * bj * 8) = tr8x8(w, fr);
.LBB0_156:
	s_or_b64 exec, exec, s[10:11]
	global_store_dwordx4 v[138:139], v[128:131], off offset:1024
	s_nop 1
	v_cvt_pk_bf16_f32 v128, v108, v109
	v_cvt_pk_bf16_f32 v129, v110, v111
	v_cvt_pk_bf16_f32 v130, v104, v105
	v_cvt_pk_bf16_f32 v131, v106, v107
	v_cndmask_b32_e64 v138, v128, v130, s[8:9]
	v_cndmask_b32_e64 v139, v129, v131, s[8:9]
	s_nop 1
	v_mov_b32_dpp v138, v138 row_half_mirror row_mask:0xf bank_mask:0xf
	s_nop 1
	v_mov_b32_dpp v138, v138 quad_perm:[3,2,1,0] row_mask:0xf bank_mask:0xf
	s_nop 1
	v_mov_b32_dpp v139, v139 row_half_mirror row_mask:0xf bank_mask:0xf
	s_nop 1
	v_mov_b32_dpp v139, v139 quad_perm:[3,2,1,0] row_mask:0xf bank_mask:0xf
	s_waitcnt lgkmcnt(0)
	v_cndmask_b32_e64 v130, v130, v138, s[8:9]
	v_cndmask_b32_e64 v131, v131, v139, s[8:9]
	v_cndmask_b32_e64 v129, v139, v129, s[8:9]
	v_cndmask_b32_e64 v128, v138, v128, s[8:9]
	v_cndmask_b32_e64 v138, v128, v129, s[6:7]
	v_cndmask_b32_e64 v139, v130, v131, s[6:7]
	s_nop 1
	v_mov_b32_dpp v143, v138 quad_perm:[2,3,0,1] row_mask:0xf bank_mask:0xf
	s_nop 1
	v_mov_b32_dpp v139, v139 quad_perm:[2,3,0,1] row_mask:0xf bank_mask:0xf
	s_waitcnt lgkmcnt(0)
	v_cndmask_b32_e64 v142, v129, v143, s[6:7]
	v_cndmask_b32_e64 v138, v131, v139, s[6:7]
	v_cndmask_b32_e64 v139, v139, v130, s[6:7]
	v_cndmask_b32_e64 v159, v143, v128, s[6:7]
	s_nop 1
	v_mov_b32_dpp v176, v159 quad_perm:[1,0,3,2] row_mask:0xf bank_mask:0xf
	s_nop 1
	v_mov_b32_dpp v175, v142 quad_perm:[1,0,3,2] row_mask:0xf bank_mask:0xf
	s_nop 1
	v_mov_b32_dpp v160, v139 quad_perm:[1,0,3,2] row_mask:0xf bank_mask:0xf
	s_nop 1
	v_mov_b32_dpp v143, v138 quad_perm:[1,0,3,2] row_mask:0xf bank_mask:0xf
	s_and_saveexec_b64 s[10:11], vcc
	s_xor_b64 s[10:11], exec, s[10:11]
	s_cbranch_execz .LBB0_158
	s_waitcnt lgkmcnt(0)
	v_lshrrev_b32_e32 v128, 16, v176
	v_lshrrev_b32_e32 v129, 16, v175
	v_lshrrev_b32_e32 v130, 16, v160
	v_lshrrev_b32_e32 v131, 16, v143
	v_and_or_b32 v128, v159, s21, v128
	v_and_or_b32 v129, v142, s21, v129
	v_and_or_b32 v130, v139, s21, v130
	v_and_or_b32 v131, v138, s21, v131

; DI unsigned pk2(float lo, float hi) { f32x2 v = {lo, hi}; bf16x2_t b = __builtin_convertvector(v, bf16x2_t); return __builtin_bit_cast(unsigned, b); }
; DI u32x4 tr8x8(u32x4 w, int lane) {
;     { const bool b = (lane & 4) != 0;
;       const unsigned s0 = b ? w.x : w.z, s1 = b ? w.y : w.w, r0 = __shfl_xor(s0, 4), r1 = __shfl_xor(s1, 4);
;       if (b) { w.x = r0; w.y = r1; } else { w.z = r0; w.w = r1; } }
;     { const bool b = (lane & 2) != 0;
;       const unsigned s0 = b ? w.x : w.y, s1 = b ? w.z : w.w, r0 = __shfl_xor(s0, 2), r1 = __shfl_xor(s1, 2);
;       if (b) { w.x = r0; w.z = r1; } else { w.y = r0; w.w = r1; } }
;     { const bool b = (lane & 1) != 0;
;       const unsigned p0 = __shfl_xor(w.x, 1), p1 = __shfl_xor(w.y, 1), p2 = __shfl_xor(w.z, 1), p3 = __shfl_xor(w.w, 1);
;       if (b) { w.x = (p0 >> 16) | (w.x & 0xffff0000u); w.y = (p1 >> 16) | (w.y & 0xffff0000u); w.z = (p2 >> 16) | (w.z & 0xffff0000u); w.w = (p3 >> 16) | (w.w & 0xffff0000u); }
;       else   { w.x = (w.x & 0xffffu) | (p0 << 16); w.y = (w.y & 0xffffu) | (p1 << 16); w.z = (w.z & 0xffffu) | (p2 << 16); w.w = (w.w & 0xffffu) | (p3 << 16); } }
;     DI void operator()(const f32x4 (&acc)[2][2][4][2], const Unit& u, int wr, int wc, int fr, int fq) const {
;     ...
;                         bf16_t* t = vt + (((size_t)((row >> 6) * 4 + head) * 8 + ((row >> 3) & 7)) * 128 + f0 + (fr & 7)) * 8;
; #pragma unroll
;                         for (int bj = 0; bj < 2; ++bj) {
;                             const f32x4 x0 = acc[ai][bj][m][0], x1 = acc[ai][bj][m][1];
;                             u32x4 w; w.x = pk2(x0[0], x0[1]); w.y = pk2(x0[2], x0[3]); w.z = pk2(x1[0], x1[1]); w.w = pk2(x1[2], x1[3]);
;                             *(u32x4*)(t + 64 * bj * 8) = tr8x8(w, fr);
.LBB0_160:
	s_or_b64 exec, exec, s[10:11]
	v_add_u32_e32 v142, 16, v158
	v_ashrrev_i32_e32 v138, 4, v142
	v_and_or_b32 v138, v138, -4, s19
	v_ashrrev_i32_e32 v139, 31, v138
	v_lshlrev_b32_e32 v142, 4, v142
	s_waitcnt lgkmcnt(0)
	v_and_b32_e32 v160, 0x380, v142
	v_lshlrev_b64 v[138:139], 14, v[138:139]
	v_lshl_add_u64 v[142:143], v[132:133], 0, v[160:161]
	v_lshl_add_u64 v[138:139], s[46:47], 0, v[138:139]
	v_lshl_add_u64 v[138:139], v[142:143], 4, v[138:139]
	global_store_dwordx4 v[138:139], v[128:131], off
	s_nop 1
	v_cvt_pk_bf16_f32 v128, v100, v101
	v_cvt_pk_bf16_f32 v129, v102, v103
	v_cvt_pk_bf16_f32 v130, v96, v97
	v_cvt_pk_bf16_f32 v131, v98, v99
	v_cndmask_b32_e64 v142, v128, v130, s[8:9]
	v_cndmask_b32_e64 v143, v129, v131, s[8:9]
	s_nop 1
	v_mov_b32_dpp v142, v142 row_half_mirror row_mask:0xf bank_mask:0xf
	s_nop 1
	v_mov_b32_dpp v142, v142 quad_perm:[3,2,1,0] row_mask:0xf bank_mask:0xf
	s_nop 1
	v_mov_b32_dpp v143, v143 row_half_mirror row_mask:0xf bank_mask:0xf
	s_nop 1
	v_mov_b32_dpp v143, v143 quad_perm:[3,2,1,0] row_mask:0xf bank_mask:0xf
	s_waitcnt lgkmcnt(0)
	v_cndmask_b32_e64 v130, v130, v142, s[8:9]
	v_cndmask_b32_e64 v131, v131, v143, s[8:9]
	v_cndmask_b32_e64 v129, v143, v129, s[8:9]
	v_cndmask_b32_e64 v128, v142, v128, s[8:9]
	v_cndmask_b32_e64 v142, v128, v129, s[6:7]
	v_cndmask_b32_e64 v143, v130, v131, s[6:7]
	s_nop 1
	v_mov_b32_dpp v160, v142 quad_perm:[2,3,0,1] row_mask:0xf bank_mask:0xf
	s_nop 1
	v_mov_b32_dpp v143, v143 quad_perm:[2,3,0,1] row_mask:0xf bank_mask:0xf
	s_waitcnt lgkmcnt(0)
	v_cndmask_b32_e64 v159, v129, v160, s[6:7]
	v_cndmask_b32_e64 v142, v131, v143, s[6:7]
	v_cndmask_b32_e64 v143, v143, v130, s[6:7]
	v_cndmask_b32_e64 v175, v160, v128, s[6:7]
	s_nop 1
	v_mov_b32_dpp v178, v175 quad_perm:[1,0,3,2] row_mask:0xf bank_mask:0xf
	s_nop 1
	v_mov_b32_dpp v177, v159 quad_perm:[1,0,3,2] row_mask:0xf bank_mask:0xf
	s_nop 1
	v_mov_b32_dpp v176, v143 quad_perm:[1,0,3,2] row_mask:0xf bank_mask:0xf
	s_nop 1
	v_mov_b32_dpp v160, v142 quad_perm:[1,0,3,2] row_mask:0xf bank_mask:0xf
	s_and_saveexec_b64 s[10:11], vcc
	s_xor_b64 s[10:11], exec, s[10:11]
	s_cbranch_execz .LBB0_162
	s_waitcnt lgkmcnt(0)
	v_lshrrev_b32_e32 v128, 16, v178
	v_lshrrev_b32_e32 v129, 16, v177
	v_lshrrev_b32_e32 v130, 16, v176
	v_lshrrev_b32_e32 v131, 16, v160
	v_and_or_b32 v128, v175, s21, v128
	v_and_or_b32 v129, v159, s21, v129
	v_and_or_b32 v130, v143, s21, v130
	v_and_or_b32 v131, v142, s21, v131

; DI unsigned pk2(float lo, float hi) { f32x2 v = {lo, hi}; bf16x2_t b = __builtin_convertvector(v, bf16x2_t); return __builtin_bit_cast(unsigned, b); }
; DI u32x4 tr8x8(u32x4 w, int lane) {
;     { const bool b = (lane & 4) != 0;
;       const unsigned s0 = b ? w.x : w.z, s1 = b ? w.y : w.w, r0 = __shfl_xor(s0, 4), r1 = __shfl_xor(s1, 4);
;       if (b) { w.x = r0; w.y = r1; } else { w.z = r0; w.w = r1; } }
;     { const bool b = (lane & 2) != 0;
;       const unsigned s0 = b ? w.x : w.y, s1 = b ? w.z : w.w, r0 = __shfl_xor(s0, 2), r1 = __shfl_xor(s1, 2);
;       if (b) { w.x = r0; w.z = r1; } else { w.y = r0; w.w = r1; } }
;     { const bool b = (lane & 1) != 0;
;       const unsigned p0 = __shfl_xor(w.x, 1), p1 = __shfl_xor(w.y, 1), p2 = __shfl_xor(w.z, 1), p3 = __shfl_xor(w.w, 1);
;       if (b) { w.x = (p0 >> 16) | (w.x & 0xffff0000u); w.y = (p1 >> 16) | (w.y & 0xffff0000u); w.z = (p2 >> 16) | (w.z & 0xffff0000u); w.w = (p3 >> 16) | (w.w & 0xffff0000u); }
;       else   { w.x = (w.x & 0xffffu) | (p0 << 16); w.y = (w.y & 0xffffu) | (p1 << 16); w.z = (w.z & 0xffffu) | (p2 << 16); w.w = (w.w & 0xffffu) | (p3 << 16); } }
;     DI void operator()(const f32x4 (&acc)[2][2][4][2], const Unit& u, int wr, int wc, int fr, int fq) const {
;     ...
;                         bf16_t* t = vt + (((size_t)((row >> 6) * 4 + head) * 8 + ((row >> 3) & 7)) * 128 + f0 + (fr & 7)) * 8;
; #pragma unroll
;                         for (int bj = 0; bj < 2; ++bj) {
;                             const f32x4 x0 = acc[ai][bj][m][0], x1 = acc[ai][bj][m][1];
;                             u32x4 w; w.x = pk2(x0[0], x0[1]); w.y = pk2(x0[2], x0[3]); w.z = pk2(x1[0], x1[1]); w.w = pk2(x1[2], x1[3]);
;                             *(u32x4*)(t + 64 * bj * 8) = tr8x8(w, fr);
.LBB0_164:
	s_or_b64 exec, exec, s[10:11]
	global_store_dwordx4 v[138:139], v[128:131], off offset:1024
	s_nop 1
	v_cvt_pk_bf16_f32 v128, v92, v93
	v_cvt_pk_bf16_f32 v129, v94, v95
	v_cvt_pk_bf16_f32 v130, v88, v89
	v_cvt_pk_bf16_f32 v131, v90, v91
	v_cndmask_b32_e64 v138, v128, v130, s[8:9]
	v_cndmask_b32_e64 v139, v129, v131, s[8:9]
	s_nop 1
	v_mov_b32_dpp v138, v138 row_half_mirror row_mask:0xf bank_mask:0xf
	s_nop 1
	v_mov_b32_dpp v138, v138 quad_perm:[3,2,1,0] row_mask:0xf bank_mask:0xf
	s_nop 1
	v_mov_b32_dpp v139, v139 row_half_mirror row_mask:0xf bank_mask:0xf
	s_nop 1
	v_mov_b32_dpp v139, v139 quad_perm:[3,2,1,0] row_mask:0xf bank_mask:0xf
	s_waitcnt lgkmcnt(0)
	v_cndmask_b32_e64 v130, v130, v138, s[8:9]
	v_cndmask_b32_e64 v131, v131, v139, s[8:9]
	v_cndmask_b32_e64 v129, v139, v129, s[8:9]
	v_cndmask_b32_e64 v128, v138, v128, s[8:9]
	v_cndmask_b32_e64 v138, v128, v129, s[6:7]
	v_cndmask_b32_e64 v139, v130, v131, s[6:7]
	s_nop 1
	v_mov_b32_dpp v143, v138 quad_perm:[2,3,0,1] row_mask:0xf bank_mask:0xf
	s_nop 1
	v_mov_b32_dpp v139, v139 quad_perm:[2,3,0,1] row_mask:0xf bank_mask:0xf
	s_waitcnt lgkmcnt(0)
	v_cndmask_b32_e64 v142, v129, v143, s[6:7]
	v_cndmask_b32_e64 v138, v131, v139, s[6:7]
	v_cndmask_b32_e64 v139, v139, v130, s[6:7]
	v_cndmask_b32_e64 v159, v143, v128, s[6:7]
	s_nop 1
	v_mov_b32_dpp v176, v159 quad_perm:[1,0,3,2] row_mask:0xf bank_mask:0xf
	s_nop 1
	v_mov_b32_dpp v175, v142 quad_perm:[1,0,3,2] row_mask:0xf bank_mask:0xf
	s_nop 1
	v_mov_b32_dpp v160, v139 quad_perm:[1,0,3,2] row_mask:0xf bank_mask:0xf
	s_nop 1
	v_mov_b32_dpp v143, v138 quad_perm:[1,0,3,2] row_mask:0xf bank_mask:0xf
	s_and_saveexec_b64 s[10:11], vcc
	s_xor_b64 s[10:11], exec, s[10:11]
	s_cbranch_execz .LBB0_166
	s_waitcnt lgkmcnt(0)
	v_lshrrev_b32_e32 v128, 16, v176
	v_lshrrev_b32_e32 v129, 16, v175
	v_lshrrev_b32_e32 v130, 16, v160
	v_lshrrev_b32_e32 v131, 16, v143
	v_and_or_b32 v128, v159, s21, v128
	v_and_or_b32 v129, v142, s21, v129
	v_and_or_b32 v130, v139, s21, v130
	v_and_or_b32 v131, v138, s21, v131

; DI unsigned pk2(float lo, float hi) { f32x2 v = {lo, hi}; bf16x2_t b = __builtin_convertvector(v, bf16x2_t); return __builtin_bit_cast(unsigned, b); }
; DI u32x4 tr8x8(u32x4 w, int lane) {
;     { const bool b = (lane & 4) != 0;
;       const unsigned s0 = b ? w.x : w.z, s1 = b ? w.y : w.w, r0 = __shfl_xor(s0, 4), r1 = __shfl_xor(s1, 4);
;       if (b) { w.x = r0; w.y = r1; } else { w.z = r0; w.w = r1; } }
;     { const bool b = (lane & 2) != 0;
;       const unsigned s0 = b ? w.x : w.y, s1 = b ? w.z : w.w, r0 = __shfl_xor(s0, 2), r1 = __shfl_xor(s1, 2);
;       if (b) { w.x = r0; w.z = r1; } else { w.y = r0; w.w = r1; } }
;     { const bool b = (lane & 1) != 0;
;       const unsigned p0 = __shfl_xor(w.x, 1), p1 = __shfl_xor(w.y, 1), p2 = __shfl_xor(w.z, 1), p3 = __shfl_xor(w.w, 1);
;       if (b) { w.x = (p0 >> 16) | (w.x & 0xffff0000u); w.y = (p1 >> 16) | (w.y & 0xffff0000u); w.z = (p2 >> 16) | (w.z & 0xffff0000u); w.w = (p3 >> 16) | (w.w & 0xffff0000u); }
;       else   { w.x = (w.x & 0xffffu) | (p0 << 16); w.y = (w.y & 0xffffu) | (p1 << 16); w.z = (w.z & 0xffffu) | (p2 << 16); w.w = (w.w & 0xffffu) | (p3 << 16); } }
;     DI void operator()(const f32x4 (&acc)[2][2][4][2], const Unit& u, int wr, int wc, int fr, int fq) const {
;     ...
;                         bf16_t* t = vt + (((size_t)((row >> 6) * 4 + head) * 8 + ((row >> 3) & 7)) * 128 + f0 + (fr & 7)) * 8;
; #pragma unroll
;                         for (int bj = 0; bj < 2; ++bj) {
;                             const f32x4 x0 = acc[ai][bj][m][0], x1 = acc[ai][bj][m][1];
;                             u32x4 w; w.x = pk2(x0[0], x0[1]); w.y = pk2(x0[2], x0[3]); w.z = pk2(x1[0], x1[1]); w.w = pk2(x1[2], x1[3]);
;                             *(u32x4*)(t + 64 * bj * 8) = tr8x8(w, fr);
.LBB0_168:
	s_or_b64 exec, exec, s[10:11]
	v_add_u32_e32 v142, 32, v158
	v_ashrrev_i32_e32 v138, 4, v142
	v_and_or_b32 v138, v138, -4, s19
	v_ashrrev_i32_e32 v139, 31, v138
	v_lshlrev_b32_e32 v142, 4, v142
	s_waitcnt lgkmcnt(0)
	v_and_b32_e32 v160, 0x380, v142
	v_lshlrev_b64 v[138:139], 14, v[138:139]
	v_lshl_add_u64 v[142:143], v[132:133], 0, v[160:161]
	v_lshl_add_u64 v[138:139], s[46:47], 0, v[138:139]
	v_lshl_add_u64 v[138:139], v[142:143], 4, v[138:139]
	global_store_dwordx4 v[138:139], v[128:131], off
	s_nop 1
	v_cvt_pk_bf16_f32 v128, v84, v85
	v_cvt_pk_bf16_f32 v129, v86, v87
	v_cvt_pk_bf16_f32 v130, v80, v81
	v_cvt_pk_bf16_f32 v131, v82, v83
	v_cndmask_b32_e64 v142, v128, v130, s[8:9]
	v_cndmask_b32_e64 v143, v129, v131, s[8:9]
	s_nop 1
	v_mov_b32_dpp v142, v142 row_half_mirror row_mask:0xf bank_mask:0xf
	s_nop 1
	v_mov_b32_dpp v142, v142 quad_perm:[3,2,1,0] row_mask:0xf bank_mask:0xf
	s_nop 1
	v_mov_b32_dpp v143, v143 row_half_mirror row_mask:0xf bank_mask:0xf
	s_nop 1
	v_mov_b32_dpp v143, v143 quad_perm:[3,2,1,0] row_mask:0xf bank_mask:0xf
	s_waitcnt lgkmcnt(0)
	v_cndmask_b32_e64 v130, v130, v142, s[8:9]
	v_cndmask_b32_e64 v131, v131, v143, s[8:9]
	v_cndmask_b32_e64 v129, v143, v129, s[8:9]
	v_cndmask_b32_e64 v128, v142, v128, s[8:9]
	v_cndmask_b32_e64 v142, v128, v129, s[6:7]
	v_cndmask_b32_e64 v143, v130, v131, s[6:7]
	s_nop 1
	v_mov_b32_dpp v160, v142 quad_perm:[2,3,0,1] row_mask:0xf bank_mask:0xf
	s_nop 1
	v_mov_b32_dpp v143, v143 quad_perm:[2,3,0,1] row_mask:0xf bank_mask:0xf
	s_waitcnt lgkmcnt(0)
	v_cndmask_b32_e64 v159, v129, v160, s[6:7]
	v_cndmask_b32_e64 v142, v131, v143, s[6:7]
	v_cndmask_b32_e64 v143, v143, v130, s[6:7]
	v_cndmask_b32_e64 v175, v160, v128, s[6:7]
	s_nop 1
	v_mov_b32_dpp v178, v175 quad_perm:[1,0,3,2] row_mask:0xf bank_mask:0xf
	s_nop 1
	v_mov_b32_dpp v177, v159 quad_perm:[1,0,3,2] row_mask:0xf bank_mask:0xf
	s_nop 1
	v_mov_b32_dpp v176, v143 quad_perm:[1,0,3,2] row_mask:0xf bank_mask:0xf
	s_nop 1
	v_mov_b32_dpp v160, v142 quad_perm:[1,0,3,2] row_mask:0xf bank_mask:0xf
	s_and_saveexec_b64 s[10:11], vcc
	s_xor_b64 s[10:11], exec, s[10:11]
	s_cbranch_execz .LBB0_170
	s_waitcnt lgkmcnt(0)
	v_lshrrev_b32_e32 v128, 16, v178
	v_lshrrev_b32_e32 v129, 16, v177
	v_lshrrev_b32_e32 v130, 16, v176
	v_lshrrev_b32_e32 v131, 16, v160
	v_and_or_b32 v128, v175, s21, v128
	v_and_or_b32 v129, v159, s21, v129
	v_and_or_b32 v130, v143, s21, v130
	v_and_or_b32 v131, v142, s21, v131

; DI unsigned pk2(float lo, float hi) { f32x2 v = {lo, hi}; bf16x2_t b = __builtin_convertvector(v, bf16x2_t); return __builtin_bit_cast(unsigned, b); }
; DI u32x4 tr8x8(u32x4 w, int lane) {
;     { const bool b = (lane & 4) != 0;
;       const unsigned s0 = b ? w.x : w.z, s1 = b ? w.y : w.w, r0 = __shfl_xor(s0, 4), r1 = __shfl_xor(s1, 4);
;       if (b) { w.x = r0; w.y = r1; } else { w.z = r0; w.w = r1; } }
;     { const bool b = (lane & 2) != 0;
;       const unsigned s0 = b ? w.x : w.y, s1 = b ? w.z : w.w, r0 = __shfl_xor(s0, 2), r1 = __shfl_xor(s1, 2);
;       if (b) { w.x = r0; w.z = r1; } else { w.y = r0; w.w = r1; } }
;     { const bool b = (lane & 1) != 0;
;       const unsigned p0 = __shfl_xor(w.x, 1), p1 = __shfl_xor(w.y, 1), p2 = __shfl_xor(w.z, 1), p3 = __shfl_xor(w.w, 1);
;       if (b) { w.x = (p0 >> 16) | (w.x & 0xffff0000u); w.y = (p1 >> 16) | (w.y & 0xffff0000u); w.z = (p2 >> 16) | (w.z & 0xffff0000u); w.w = (p3 >> 16) | (w.w & 0xffff0000u); }
;       else   { w.x = (w.x & 0xffffu) | (p0 << 16); w.y = (w.y & 0xffffu) | (p1 << 16); w.z = (w.z & 0xffffu) | (p2 << 16); w.w = (w.w & 0xffffu) | (p3 << 16); } }
;     DI void operator()(const f32x4 (&acc)[2][2][4][2], const Unit& u, int wr, int wc, int fr, int fq) const {
;     ...
;                         bf16_t* t = vt + (((size_t)((row >> 6) * 4 + head) * 8 + ((row >> 3) & 7)) * 128 + f0 + (fr & 7)) * 8;
; #pragma unroll
;                         for (int bj = 0; bj < 2; ++bj) {
;                             const f32x4 x0 = acc[ai][bj][m][0], x1 = acc[ai][bj][m][1];
;                             u32x4 w; w.x = pk2(x0[0], x0[1]); w.y = pk2(x0[2], x0[3]); w.z = pk2(x1[0], x1[1]); w.w = pk2(x1[2], x1[3]);
;                             *(u32x4*)(t + 64 * bj * 8) = tr8x8(w, fr);
.LBB0_172:
	s_or_b64 exec, exec, s[10:11]
	global_store_dwordx4 v[138:139], v[128:131], off offset:1024
	s_nop 1
	v_cvt_pk_bf16_f32 v128, v76, v77
	v_cvt_pk_bf16_f32 v129, v78, v79
	v_cvt_pk_bf16_f32 v130, v72, v73
	v_cvt_pk_bf16_f32 v131, v74, v75
	v_cndmask_b32_e64 v138, v128, v130, s[8:9]
	v_cndmask_b32_e64 v139, v129, v131, s[8:9]
	s_nop 1
	v_mov_b32_dpp v138, v138 row_half_mirror row_mask:0xf bank_mask:0xf
	s_nop 1
	v_mov_b32_dpp v138, v138 quad_perm:[3,2,1,0] row_mask:0xf bank_mask:0xf
	s_nop 1
	v_mov_b32_dpp v139, v139 row_half_mirror row_mask:0xf bank_mask:0xf
	s_nop 1
	v_mov_b32_dpp v139, v139 quad_perm:[3,2,1,0] row_mask:0xf bank_mask:0xf
	s_waitcnt lgkmcnt(0)
	v_cndmask_b32_e64 v130, v130, v138, s[8:9]
	v_cndmask_b32_e64 v131, v131, v139, s[8:9]
	v_cndmask_b32_e64 v129, v139, v129, s[8:9]
	v_cndmask_b32_e64 v128, v138, v128, s[8:9]
	v_cndmask_b32_e64 v138, v128, v129, s[6:7]
	v_cndmask_b32_e64 v139, v130, v131, s[6:7]
	s_nop 1
	v_mov_b32_dpp v143, v138 quad_perm:[2,3,0,1] row_mask:0xf bank_mask:0xf
	s_nop 1
	v_mov_b32_dpp v139, v139 quad_perm:[2,3,0,1] row_mask:0xf bank_mask:0xf
	s_waitcnt lgkmcnt(0)
	v_cndmask_b32_e64 v142, v129, v143, s[6:7]
	v_cndmask_b32_e64 v138, v131, v139, s[6:7]
	v_cndmask_b32_e64 v139, v139, v130, s[6:7]
	v_cndmask_b32_e64 v159, v143, v128, s[6:7]
	s_nop 1
	v_mov_b32_dpp v176, v159 quad_perm:[1,0,3,2] row_mask:0xf bank_mask:0xf
	s_nop 1
	v_mov_b32_dpp v175, v142 quad_perm:[1,0,3,2] row_mask:0xf bank_mask:0xf
	s_nop 1
	v_mov_b32_dpp v160, v139 quad_perm:[1,0,3,2] row_mask:0xf bank_mask:0xf
	s_nop 1
	v_mov_b32_dpp v143, v138 quad_perm:[1,0,3,2] row_mask:0xf bank_mask:0xf
	s_and_saveexec_b64 s[10:11], vcc
	s_xor_b64 s[10:11], exec, s[10:11]
	s_cbranch_execz .LBB0_174
	s_waitcnt lgkmcnt(0)
	v_lshrrev_b32_e32 v128, 16, v176
	v_lshrrev_b32_e32 v129, 16, v175
	v_lshrrev_b32_e32 v130, 16, v160
	v_lshrrev_b32_e32 v131, 16, v143
	v_and_or_b32 v128, v159, s21, v128
	v_and_or_b32 v129, v142, s21, v129
	v_and_or_b32 v130, v139, s21, v130
	v_and_or_b32 v131, v138, s21, v131

; DI unsigned pk2(float lo, float hi) { f32x2 v = {lo, hi}; bf16x2_t b = __builtin_convertvector(v, bf16x2_t); return __builtin_bit_cast(unsigned, b); }
; DI u32x4 tr8x8(u32x4 w, int lane) {
;     { const bool b = (lane & 4) != 0;
;       const unsigned s0 = b ? w.x : w.z, s1 = b ? w.y : w.w, r0 = __shfl_xor(s0, 4), r1 = __shfl_xor(s1, 4);
;       if (b) { w.x = r0; w.y = r1; } else { w.z = r0; w.w = r1; } }
;     { const bool b = (lane & 2) != 0;
;       const unsigned s0 = b ? w.x : w.y, s1 = b ? w.z : w.w, r0 = __shfl_xor(s0, 2), r1 = __shfl_xor(s1, 2);
;       if (b) { w.x = r0; w.z = r1; } else { w.y = r0; w.w = r1; } }
;     { const bool b = (lane & 1) != 0;
;       const unsigned p0 = __shfl_xor(w.x, 1), p1 = __shfl_xor(w.y, 1), p2 = __shfl_xor(w.z, 1), p3 = __shfl_xor(w.w, 1);
;       if (b) { w.x = (p0 >> 16) | (w.x & 0xffff0000u); w.y = (p1 >> 16) | (w.y & 0xffff0000u); w.z = (p2 >> 16) | (w.z & 0xffff0000u); w.w = (p3 >> 16) | (w.w & 0xffff0000u); }
;       else   { w.x = (w.x & 0xffffu) | (p0 << 16); w.y = (w.y & 0xffffu) | (p1 << 16); w.z = (w.z & 0xffffu) | (p2 << 16); w.w = (w.w & 0xffffu) | (p3 << 16); } }
;     DI void operator()(const f32x4 (&acc)[2][2][4][2], const Unit& u, int wr, int wc, int fr, int fq) const {
;     ...
;                         bf16_t* t = vt + (((size_t)((row >> 6) * 4 + head) * 8 + ((row >> 3) & 7)) * 128 + f0 + (fr & 7)) * 8;
; #pragma unroll
;                         for (int bj = 0; bj < 2; ++bj) {
;                             const f32x4 x0 = acc[ai][bj][m][0], x1 = acc[ai][bj][m][1];
;                             u32x4 w; w.x = pk2(x0[0], x0[1]); w.y = pk2(x0[2], x0[3]); w.z = pk2(x1[0], x1[1]); w.w = pk2(x1[2], x1[3]);
;                             *(u32x4*)(t + 64 * bj * 8) = tr8x8(w, fr);
.LBB0_176:
	s_or_b64 exec, exec, s[10:11]
	v_add_u32_e32 v142, 48, v158
	v_ashrrev_i32_e32 v138, 4, v142
	v_and_or_b32 v138, v138, -4, s19
	v_ashrrev_i32_e32 v139, 31, v138
	v_lshlrev_b32_e32 v142, 4, v142
	s_waitcnt lgkmcnt(0)
	v_and_b32_e32 v160, 0x380, v142
	v_lshlrev_b64 v[138:139], 14, v[138:139]
	v_lshl_add_u64 v[142:143], v[132:133], 0, v[160:161]
	v_lshl_add_u64 v[138:139], s[46:47], 0, v[138:139]
	v_lshl_add_u64 v[138:139], v[142:143], 4, v[138:139]
	global_store_dwordx4 v[138:139], v[128:131], off
	s_nop 1
	v_cvt_pk_bf16_f32 v128, v68, v69
	v_cvt_pk_bf16_f32 v129, v70, v71
	v_cvt_pk_bf16_f32 v130, v64, v65
	v_cvt_pk_bf16_f32 v131, v66, v67
	v_cndmask_b32_e64 v142, v128, v130, s[8:9]
	v_cndmask_b32_e64 v143, v129, v131, s[8:9]
	s_nop 1
	v_mov_b32_dpp v142, v142 row_half_mirror row_mask:0xf bank_mask:0xf
	s_nop 1
	v_mov_b32_dpp v142, v142 quad_perm:[3,2,1,0] row_mask:0xf bank_mask:0xf
	s_nop 1
	v_mov_b32_dpp v143, v143 row_half_mirror row_mask:0xf bank_mask:0xf
	s_nop 1
	v_mov_b32_dpp v143, v143 quad_perm:[3,2,1,0] row_mask:0xf bank_mask:0xf
	s_waitcnt lgkmcnt(0)
	v_cndmask_b32_e64 v130, v130, v142, s[8:9]
	v_cndmask_b32_e64 v131, v131, v143, s[8:9]
	v_cndmask_b32_e64 v129, v143, v129, s[8:9]
	v_cndmask_b32_e64 v128, v142, v128, s[8:9]
	v_cndmask_b32_e64 v142, v128, v129, s[6:7]
	v_cndmask_b32_e64 v143, v130, v131, s[6:7]
	s_nop 1
	v_mov_b32_dpp v160, v142 quad_perm:[2,3,0,1] row_mask:0xf bank_mask:0xf
	s_nop 1
	v_mov_b32_dpp v143, v143 quad_perm:[2,3,0,1] row_mask:0xf bank_mask:0xf
	s_waitcnt lgkmcnt(0)
	v_cndmask_b32_e64 v159, v129, v160, s[6:7]
	v_cndmask_b32_e64 v142, v131, v143, s[6:7]
	v_cndmask_b32_e64 v143, v143, v130, s[6:7]
	v_cndmask_b32_e64 v175, v160, v128, s[6:7]
	s_nop 1
	v_mov_b32_dpp v178, v175 quad_perm:[1,0,3,2] row_mask:0xf bank_mask:0xf
	s_nop 1
	v_mov_b32_dpp v177, v159 quad_perm:[1,0,3,2] row_mask:0xf bank_mask:0xf
	s_nop 1
	v_mov_b32_dpp v176, v143 quad_perm:[1,0,3,2] row_mask:0xf bank_mask:0xf
	s_nop 1
	v_mov_b32_dpp v160, v142 quad_perm:[1,0,3,2] row_mask:0xf bank_mask:0xf
	s_and_saveexec_b64 s[10:11], vcc
	s_xor_b64 s[10:11], exec, s[10:11]
	s_cbranch_execz .LBB0_178
	s_waitcnt lgkmcnt(0)
	v_lshrrev_b32_e32 v128, 16, v178
	v_lshrrev_b32_e32 v129, 16, v177
	v_lshrrev_b32_e32 v130, 16, v176
	v_lshrrev_b32_e32 v131, 16, v160
	v_and_or_b32 v128, v175, s21, v128
	v_and_or_b32 v129, v159, s21, v129
	v_and_or_b32 v130, v143, s21, v130
	v_and_or_b32 v131, v142, s21, v131

; DI unsigned pk2(float lo, float hi) { f32x2 v = {lo, hi}; bf16x2_t b = __builtin_convertvector(v, bf16x2_t); return __builtin_bit_cast(unsigned, b); }
; DI u32x4 tr8x8(u32x4 w, int lane) {
;     { const bool b = (lane & 4) != 0;
;       const unsigned s0 = b ? w.x : w.z, s1 = b ? w.y : w.w, r0 = __shfl_xor(s0, 4), r1 = __shfl_xor(s1, 4);
;       if (b) { w.x = r0; w.y = r1; } else { w.z = r0; w.w = r1; } }
;     { const bool b = (lane & 2) != 0;
;       const unsigned s0 = b ? w.x : w.y, s1 = b ? w.z : w.w, r0 = __shfl_xor(s0, 2), r1 = __shfl_xor(s1, 2);
;       if (b) { w.x = r0; w.z = r1; } else { w.y = r0; w.w = r1; } }
;     { const bool b = (lane & 1) != 0;
;       const unsigned p0 = __shfl_xor(w.x, 1), p1 = __shfl_xor(w.y, 1), p2 = __shfl_xor(w.z, 1), p3 = __shfl_xor(w.w, 1);
;       if (b) { w.x = (p0 >> 16) | (w.x & 0xffff0000u); w.y = (p1 >> 16) | (w.y & 0xffff0000u); w.z = (p2 >> 16) | (w.z & 0xffff0000u); w.w = (p3 >> 16) | (w.w & 0xffff0000u); }
;       else   { w.x = (w.x & 0xffffu) | (p0 << 16); w.y = (w.y & 0xffffu) | (p1 << 16); w.z = (w.z & 0xffffu) | (p2 << 16); w.w = (w.w & 0xffffu) | (p3 << 16); } }
;     DI void operator()(const f32x4 (&acc)[2][2][4][2], const Unit& u, int wr, int wc, int fr, int fq) const {
;     ...
;                         bf16_t* t = vt + (((size_t)((row >> 6) * 4 + head) * 8 + ((row >> 3) & 7)) * 128 + f0 + (fr & 7)) * 8;
; #pragma unroll
;                         for (int bj = 0; bj < 2; ++bj) {
;                             const f32x4 x0 = acc[ai][bj][m][0], x1 = acc[ai][bj][m][1];
;                             u32x4 w; w.x = pk2(x0[0], x0[1]); w.y = pk2(x0[2], x0[3]); w.z = pk2(x1[0], x1[1]); w.w = pk2(x1[2], x1[3]);
;                             *(u32x4*)(t + 64 * bj * 8) = tr8x8(w, fr);
.LBB0_180:
	s_or_b64 exec, exec, s[10:11]
	global_store_dwordx4 v[138:139], v[128:131], off offset:1024
	s_nop 1
	v_cvt_pk_bf16_f32 v128, v60, v61
	v_cvt_pk_bf16_f32 v129, v62, v63
	v_cvt_pk_bf16_f32 v130, v56, v57
	v_cvt_pk_bf16_f32 v131, v58, v59
	v_cndmask_b32_e64 v138, v128, v130, s[8:9]
	v_cndmask_b32_e64 v139, v129, v131, s[8:9]
	s_nop 1
	v_mov_b32_dpp v138, v138 row_half_mirror row_mask:0xf bank_mask:0xf
	s_nop 1
	v_mov_b32_dpp v138, v138 quad_perm:[3,2,1,0] row_mask:0xf bank_mask:0xf
	s_nop 1
	v_mov_b32_dpp v139, v139 row_half_mirror row_mask:0xf bank_mask:0xf
	s_nop 1
	v_mov_b32_dpp v139, v139 quad_perm:[3,2,1,0] row_mask:0xf bank_mask:0xf
	s_waitcnt lgkmcnt(0)
	v_cndmask_b32_e64 v130, v130, v138, s[8:9]
	v_cndmask_b32_e64 v131, v131, v139, s[8:9]
	v_cndmask_b32_e64 v129, v139, v129, s[8:9]
	v_cndmask_b32_e64 v128, v138, v128, s[8:9]
	v_cndmask_b32_e64 v138, v128, v129, s[6:7]
	v_cndmask_b32_e64 v139, v130, v131, s[6:7]
	s_nop 1
	v_mov_b32_dpp v143, v138 quad_perm:[2,3,0,1] row_mask:0xf bank_mask:0xf
	s_nop 1
	v_mov_b32_dpp v139, v139 quad_perm:[2,3,0,1] row_mask:0xf bank_mask:0xf
	s_waitcnt lgkmcnt(0)
	v_cndmask_b32_e64 v142, v129, v143, s[6:7]
	v_cndmask_b32_e64 v138, v131, v139, s[6:7]
	v_cndmask_b32_e64 v139, v139, v130, s[6:7]
	v_cndmask_b32_e64 v159, v143, v128, s[6:7]
	s_nop 1
	v_mov_b32_dpp v176, v159 quad_perm:[1,0,3,2] row_mask:0xf bank_mask:0xf
	s_nop 1
	v_mov_b32_dpp v175, v142 quad_perm:[1,0,3,2] row_mask:0xf bank_mask:0xf
	s_nop 1
	v_mov_b32_dpp v160, v139 quad_perm:[1,0,3,2] row_mask:0xf bank_mask:0xf
	s_nop 1
	v_mov_b32_dpp v143, v138 quad_perm:[1,0,3,2] row_mask:0xf bank_mask:0xf
	s_and_saveexec_b64 s[10:11], vcc
	s_xor_b64 s[10:11], exec, s[10:11]
	s_cbranch_execz .LBB0_182
	s_waitcnt lgkmcnt(0)
	v_lshrrev_b32_e32 v128, 16, v176
	v_lshrrev_b32_e32 v129, 16, v175
	v_lshrrev_b32_e32 v130, 16, v160
	v_lshrrev_b32_e32 v131, 16, v143
	v_and_or_b32 v128, v159, s21, v128
	v_and_or_b32 v129, v142, s21, v129
	v_and_or_b32 v130, v139, s21, v130
	v_and_or_b32 v131, v138, s21, v131

; DI unsigned pk2(float lo, float hi) { f32x2 v = {lo, hi}; bf16x2_t b = __builtin_convertvector(v, bf16x2_t); return __builtin_bit_cast(unsigned, b); }
; DI u32x4 tr8x8(u32x4 w, int lane) {
;     { const bool b = (lane & 4) != 0;
;       const unsigned s0 = b ? w.x : w.z, s1 = b ? w.y : w.w, r0 = __shfl_xor(s0, 4), r1 = __shfl_xor(s1, 4);
;       if (b) { w.x = r0; w.y = r1; } else { w.z = r0; w.w = r1; } }
;     { const bool b = (lane & 2) != 0;
;       const unsigned s0 = b ? w.x : w.y, s1 = b ? w.z : w.w, r0 = __shfl_xor(s0, 2), r1 = __shfl_xor(s1, 2);
;       if (b) { w.x = r0; w.z = r1; } else { w.y = r0; w.w = r1; } }
;     { const bool b = (lane & 1) != 0;
;       const unsigned p0 = __shfl_xor(w.x, 1), p1 = __shfl_xor(w.y, 1), p2 = __shfl_xor(w.z, 1), p3 = __shfl_xor(w.w, 1);
;       if (b) { w.x = (p0 >> 16) | (w.x & 0xffff0000u); w.y = (p1 >> 16) | (w.y & 0xffff0000u); w.z = (p2 >> 16) | (w.z & 0xffff0000u); w.w = (p3 >> 16) | (w.w & 0xffff0000u); }
;       else   { w.x = (w.x & 0xffffu) | (p0 << 16); w.y = (w.y & 0xffffu) | (p1 << 16); w.z = (w.z & 0xffffu) | (p2 << 16); w.w = (w.w & 0xffffu) | (p3 << 16); } }
;     DI void operator()(const f32x4 (&acc)[2][2][4][2], const Unit& u, int wr, int wc, int fr, int fq) const {
;     ...
;                         bf16_t* t = vt + (((size_t)((row >> 6) * 4 + head) * 8 + ((row >> 3) & 7)) * 128 + f0 + (fr & 7)) * 8;
; #pragma unroll
;                         for (int bj = 0; bj < 2; ++bj) {
;                             const f32x4 x0 = acc[ai][bj][m][0], x1 = acc[ai][bj][m][1];
;                             u32x4 w; w.x = pk2(x0[0], x0[1]); w.y = pk2(x0[2], x0[3]); w.z = pk2(x1[0], x1[1]); w.w = pk2(x1[2], x1[3]);
;                             *(u32x4*)(t + 64 * bj * 8) = tr8x8(w, fr);
.LBB0_184:
	s_or_b64 exec, exec, s[10:11]
	v_add_u32_e32 v138, 0x80, v158
	v_ashrrev_i32_e32 v138, 4, v138
	v_and_or_b32 v138, v138, -4, s19
	v_ashrrev_i32_e32 v139, 31, v138
	v_lshlrev_b64 v[138:139], 14, v[138:139]
	v_lshl_add_u64 v[138:139], s[46:47], 0, v[138:139]
	v_lshl_add_u64 v[134:135], v[138:139], 0, v[134:135]
	global_store_dwordx4 v[134:135], v[128:131], off
	s_nop 1
	v_cvt_pk_bf16_f32 v128, v52, v53
	v_cvt_pk_bf16_f32 v129, v54, v55
	v_cvt_pk_bf16_f32 v130, v48, v49
	v_cvt_pk_bf16_f32 v131, v50, v51
	v_cndmask_b32_e64 v138, v128, v130, s[8:9]
	v_cndmask_b32_e64 v139, v129, v131, s[8:9]
	s_nop 1
	v_mov_b32_dpp v138, v138 row_half_mirror row_mask:0xf bank_mask:0xf
	s_nop 1
	v_mov_b32_dpp v138, v138 quad_perm:[3,2,1,0] row_mask:0xf bank_mask:0xf
	s_nop 1
	v_mov_b32_dpp v139, v139 row_half_mirror row_mask:0xf bank_mask:0xf
	s_nop 1
	v_mov_b32_dpp v139, v139 quad_perm:[3,2,1,0] row_mask:0xf bank_mask:0xf
	s_waitcnt lgkmcnt(0)
	v_cndmask_b32_e64 v130, v130, v138, s[8:9]
	v_cndmask_b32_e64 v131, v131, v139, s[8:9]
	v_cndmask_b32_e64 v129, v139, v129, s[8:9]
	v_cndmask_b32_e64 v128, v138, v128, s[8:9]
	v_cndmask_b32_e64 v138, v128, v129, s[6:7]
	v_cndmask_b32_e64 v139, v130, v131, s[6:7]
	s_nop 1
	v_mov_b32_dpp v143, v138 quad_perm:[2,3,0,1] row_mask:0xf bank_mask:0xf
	s_nop 1
	v_mov_b32_dpp v139, v139 quad_perm:[2,3,0,1] row_mask:0xf bank_mask:0xf
	s_waitcnt lgkmcnt(0)
	v_cndmask_b32_e64 v142, v129, v143, s[6:7]
	v_cndmask_b32_e64 v138, v131, v139, s[6:7]
	v_cndmask_b32_e64 v139, v139, v130, s[6:7]
	v_cndmask_b32_e64 v159, v143, v128, s[6:7]
	s_nop 1
	v_mov_b32_dpp v176, v159 quad_perm:[1,0,3,2] row_mask:0xf bank_mask:0xf
	s_nop 1
	v_mov_b32_dpp v175, v142 quad_perm:[1,0,3,2] row_mask:0xf bank_mask:0xf
	s_nop 1
	v_mov_b32_dpp v160, v139 quad_perm:[1,0,3,2] row_mask:0xf bank_mask:0xf
	s_nop 1
	v_mov_b32_dpp v143, v138 quad_perm:[1,0,3,2] row_mask:0xf bank_mask:0xf
	s_and_saveexec_b64 s[10:11], vcc
	s_xor_b64 s[10:11], exec, s[10:11]
	s_cbranch_execz .LBB0_186
	s_waitcnt lgkmcnt(0)
	v_lshrrev_b32_e32 v128, 16, v176
	v_lshrrev_b32_e32 v129, 16, v175
	v_lshrrev_b32_e32 v130, 16, v160
	v_lshrrev_b32_e32 v131, 16, v143
	v_and_or_b32 v128, v159, s21, v128
	v_and_or_b32 v129, v142, s21, v129
	v_and_or_b32 v130, v139, s21, v130
	v_and_or_b32 v131, v138, s21, v131

; DI unsigned pk2(float lo, float hi) { f32x2 v = {lo, hi}; bf16x2_t b = __builtin_convertvector(v, bf16x2_t); return __builtin_bit_cast(unsigned, b); }
; DI u32x4 tr8x8(u32x4 w, int lane) {
;     { const bool b = (lane & 4) != 0;
;       const unsigned s0 = b ? w.x : w.z, s1 = b ? w.y : w.w, r0 = __shfl_xor(s0, 4), r1 = __shfl_xor(s1, 4);
;       if (b) { w.x = r0; w.y = r1; } else { w.z = r0; w.w = r1; } }
;     { const bool b = (lane & 2) != 0;
;       const unsigned s0 = b ? w.x : w.y, s1 = b ? w.z : w.w, r0 = __shfl_xor(s0, 2), r1 = __shfl_xor(s1, 2);
;       if (b) { w.x = r0; w.z = r1; } else { w.y = r0; w.w = r1; } }
;     { const bool b = (lane & 1) != 0;
;       const unsigned p0 = __shfl_xor(w.x, 1), p1 = __shfl_xor(w.y, 1), p2 = __shfl_xor(w.z, 1), p3 = __shfl_xor(w.w, 1);
;       if (b) { w.x = (p0 >> 16) | (w.x & 0xffff0000u); w.y = (p1 >> 16) | (w.y & 0xffff0000u); w.z = (p2 >> 16) | (w.z & 0xffff0000u); w.w = (p3 >> 16) | (w.w & 0xffff0000u); }
;       else   { w.x = (w.x & 0xffffu) | (p0 << 16); w.y = (w.y & 0xffffu) | (p1 << 16); w.z = (w.z & 0xffffu) | (p2 << 16); w.w = (w.w & 0xffffu) | (p3 << 16); } }
;     DI void operator()(const f32x4 (&acc)[2][2][4][2], const Unit& u, int wr, int wc, int fr, int fq) const {
;     ...
;                         bf16_t* t = vt + (((size_t)((row >> 6) * 4 + head) * 8 + ((row >> 3) & 7)) * 128 + f0 + (fr & 7)) * 8;
; #pragma unroll
;                         for (int bj = 0; bj < 2; ++bj) {
;                             const f32x4 x0 = acc[ai][bj][m][0], x1 = acc[ai][bj][m][1];
;                             u32x4 w; w.x = pk2(x0[0], x0[1]); w.y = pk2(x0[2], x0[3]); w.z = pk2(x1[0], x1[1]); w.w = pk2(x1[2], x1[3]);
;                             *(u32x4*)(t + 64 * bj * 8) = tr8x8(w, fr);
.LBB0_188:
	s_or_b64 exec, exec, s[10:11]
	global_store_dwordx4 v[134:135], v[128:131], off offset:1024
	s_nop 1
	v_cvt_pk_bf16_f32 v128, v44, v45
	v_cvt_pk_bf16_f32 v129, v46, v47
	v_cvt_pk_bf16_f32 v130, v40, v41
	v_cvt_pk_bf16_f32 v131, v42, v43
	v_cndmask_b32_e64 v134, v128, v130, s[8:9]
	v_cndmask_b32_e64 v135, v129, v131, s[8:9]
	s_nop 1
	v_mov_b32_dpp v134, v134 row_half_mirror row_mask:0xf bank_mask:0xf
	s_nop 1
	v_mov_b32_dpp v134, v134 quad_perm:[3,2,1,0] row_mask:0xf bank_mask:0xf
	s_nop 1
	v_mov_b32_dpp v135, v135 row_half_mirror row_mask:0xf bank_mask:0xf
	s_nop 1
	v_mov_b32_dpp v135, v135 quad_perm:[3,2,1,0] row_mask:0xf bank_mask:0xf
	s_waitcnt lgkmcnt(0)
	v_cndmask_b32_e64 v130, v130, v134, s[8:9]
	v_cndmask_b32_e64 v131, v131, v135, s[8:9]
	v_cndmask_b32_e64 v129, v135, v129, s[8:9]
	v_cndmask_b32_e64 v128, v134, v128, s[8:9]
	v_cndmask_b32_e64 v134, v128, v129, s[6:7]
	v_cndmask_b32_e64 v135, v130, v131, s[6:7]
	s_nop 1
	v_mov_b32_dpp v139, v134 quad_perm:[2,3,0,1] row_mask:0xf bank_mask:0xf
	s_nop 1
	v_mov_b32_dpp v135, v135 quad_perm:[2,3,0,1] row_mask:0xf bank_mask:0xf
	s_waitcnt lgkmcnt(0)
	v_cndmask_b32_e64 v138, v129, v139, s[6:7]
	v_cndmask_b32_e64 v134, v131, v135, s[6:7]
	v_cndmask_b32_e64 v135, v135, v130, s[6:7]
	v_cndmask_b32_e64 v142, v139, v128, s[6:7]
	s_nop 1
	v_mov_b32_dpp v160, v142 quad_perm:[1,0,3,2] row_mask:0xf bank_mask:0xf
	s_nop 1
	v_mov_b32_dpp v159, v138 quad_perm:[1,0,3,2] row_mask:0xf bank_mask:0xf
	s_nop 1
	v_mov_b32_dpp v143, v135 quad_perm:[1,0,3,2] row_mask:0xf bank_mask:0xf
	s_nop 1
	v_mov_b32_dpp v139, v134 quad_perm:[1,0,3,2] row_mask:0xf bank_mask:0xf
	s_and_saveexec_b64 s[10:11], vcc
	s_xor_b64 s[10:11], exec, s[10:11]
	s_cbranch_execz .LBB0_190
	s_waitcnt lgkmcnt(0)
	v_lshrrev_b32_e32 v128, 16, v160
	v_lshrrev_b32_e32 v129, 16, v159
	v_lshrrev_b32_e32 v130, 16, v143
	v_lshrrev_b32_e32 v131, 16, v139
	v_and_or_b32 v128, v142, s21, v128
	v_and_or_b32 v129, v138, s21, v129
	v_and_or_b32 v130, v135, s21, v130
	v_and_or_b32 v131, v134, s21, v131

; DI unsigned pk2(float lo, float hi) { f32x2 v = {lo, hi}; bf16x2_t b = __builtin_convertvector(v, bf16x2_t); return __builtin_bit_cast(unsigned, b); }
; DI u32x4 tr8x8(u32x4 w, int lane) {
;     { const bool b = (lane & 4) != 0;
;       const unsigned s0 = b ? w.x : w.z, s1 = b ? w.y : w.w, r0 = __shfl_xor(s0, 4), r1 = __shfl_xor(s1, 4);
;       if (b) { w.x = r0; w.y = r1; } else { w.z = r0; w.w = r1; } }
;     { const bool b = (lane & 2) != 0;
;       const unsigned s0 = b ? w.x : w.y, s1 = b ? w.z : w.w, r0 = __shfl_xor(s0, 2), r1 = __shfl_xor(s1, 2);
;       if (b) { w.x = r0; w.z = r1; } else { w.y = r0; w.w = r1; } }
;     { const bool b = (lane & 1) != 0;
;       const unsigned p0 = __shfl_xor(w.x, 1), p1 = __shfl_xor(w.y, 1), p2 = __shfl_xor(w.z, 1), p3 = __shfl_xor(w.w, 1);
;       if (b) { w.x = (p0 >> 16) | (w.x & 0xffff0000u); w.y = (p1 >> 16) | (w.y & 0xffff0000u); w.z = (p2 >> 16) | (w.z & 0xffff0000u); w.w = (p3 >> 16) | (w.w & 0xffff0000u); }
;       else   { w.x = (w.x & 0xffffu) | (p0 << 16); w.y = (w.y & 0xffffu) | (p1 << 16); w.z = (w.z & 0xffffu) | (p2 << 16); w.w = (w.w & 0xffffu) | (p3 << 16); } }
;     DI void operator()(const f32x4 (&acc)[2][2][4][2], const Unit& u, int wr, int wc, int fr, int fq) const {
;     ...
;                         bf16_t* t = vt + (((size_t)((row >> 6) * 4 + head) * 8 + ((row >> 3) & 7)) * 128 + f0 + (fr & 7)) * 8;
; #pragma unroll
;                         for (int bj = 0; bj < 2; ++bj) {
;                             const f32x4 x0 = acc[ai][bj][m][0], x1 = acc[ai][bj][m][1];
;                             u32x4 w; w.x = pk2(x0[0], x0[1]); w.y = pk2(x0[2], x0[3]); w.z = pk2(x1[0], x1[1]); w.w = pk2(x1[2], x1[3]);
;                             *(u32x4*)(t + 64 * bj * 8) = tr8x8(w, fr);
.LBB0_192:
	s_or_b64 exec, exec, s[10:11]
	v_add_u32_e32 v138, 0x90, v158
	v_ashrrev_i32_e32 v134, 4, v138
	v_and_or_b32 v134, v134, -4, s19
	v_ashrrev_i32_e32 v135, 31, v134
	v_lshlrev_b32_e32 v138, 4, v138
	s_waitcnt lgkmcnt(0)
	v_and_b32_e32 v160, 0x380, v138
	v_lshlrev_b64 v[134:135], 14, v[134:135]
	v_lshl_add_u64 v[138:139], v[132:133], 0, v[160:161]
	v_lshl_add_u64 v[134:135], s[46:47], 0, v[134:135]
	v_lshl_add_u64 v[134:135], v[138:139], 4, v[134:135]
	global_store_dwordx4 v[134:135], v[128:131], off
	s_nop 1
	v_cvt_pk_bf16_f32 v128, v36, v37
	v_cvt_pk_bf16_f32 v129, v38, v39
	v_cvt_pk_bf16_f32 v130, v32, v33
	v_cvt_pk_bf16_f32 v131, v34, v35
	v_cndmask_b32_e64 v138, v128, v130, s[8:9]
	v_cndmask_b32_e64 v139, v129, v131, s[8:9]
	s_nop 1
	v_mov_b32_dpp v138, v138 row_half_mirror row_mask:0xf bank_mask:0xf
	s_nop 1
	v_mov_b32_dpp v138, v138 quad_perm:[3,2,1,0] row_mask:0xf bank_mask:0xf
	s_nop 1
	v_mov_b32_dpp v139, v139 row_half_mirror row_mask:0xf bank_mask:0xf
	s_nop 1
	v_mov_b32_dpp v139, v139 quad_perm:[3,2,1,0] row_mask:0xf bank_mask:0xf
	s_waitcnt lgkmcnt(0)
	v_cndmask_b32_e64 v130, v130, v138, s[8:9]
	v_cndmask_b32_e64 v131, v131, v139, s[8:9]
	v_cndmask_b32_e64 v129, v139, v129, s[8:9]
	v_cndmask_b32_e64 v128, v138, v128, s[8:9]
	v_cndmask_b32_e64 v138, v128, v129, s[6:7]
	v_cndmask_b32_e64 v139, v130, v131, s[6:7]
	s_nop 1
	v_mov_b32_dpp v143, v138 quad_perm:[2,3,0,1] row_mask:0xf bank_mask:0xf
	s_nop 1
	v_mov_b32_dpp v139, v139 quad_perm:[2,3,0,1] row_mask:0xf bank_mask:0xf
	s_waitcnt lgkmcnt(0)
	v_cndmask_b32_e64 v142, v129, v143, s[6:7]
	v_cndmask_b32_e64 v138, v131, v139, s[6:7]
	v_cndmask_b32_e64 v139, v139, v130, s[6:7]
	v_cndmask_b32_e64 v159, v143, v128, s[6:7]
	s_nop 1
	v_mov_b32_dpp v176, v159 quad_perm:[1,0,3,2] row_mask:0xf bank_mask:0xf
	s_nop 1
	v_mov_b32_dpp v175, v142 quad_perm:[1,0,3,2] row_mask:0xf bank_mask:0xf
	s_nop 1
	v_mov_b32_dpp v160, v139 quad_perm:[1,0,3,2] row_mask:0xf bank_mask:0xf
	s_nop 1
	v_mov_b32_dpp v143, v138 quad_perm:[1,0,3,2] row_mask:0xf bank_mask:0xf
	s_and_saveexec_b64 s[10:11], vcc
	s_xor_b64 s[10:11], exec, s[10:11]
	s_cbranch_execz .LBB0_194
	s_waitcnt lgkmcnt(0)
	v_lshrrev_b32_e32 v128, 16, v176
	v_lshrrev_b32_e32 v129, 16, v175
	v_lshrrev_b32_e32 v130, 16, v160
	v_lshrrev_b32_e32 v131, 16, v143
	v_and_or_b32 v128, v159, s21, v128
	v_and_or_b32 v129, v142, s21, v129
	v_and_or_b32 v130, v139, s21, v130
	v_and_or_b32 v131, v138, s21, v131

; DI unsigned pk2(float lo, float hi) { f32x2 v = {lo, hi}; bf16x2_t b = __builtin_convertvector(v, bf16x2_t); return __builtin_bit_cast(unsigned, b); }
; DI u32x4 tr8x8(u32x4 w, int lane) {
;     { const bool b = (lane & 4) != 0;
;       const unsigned s0 = b ? w.x : w.z, s1 = b ? w.y : w.w, r0 = __shfl_xor(s0, 4), r1 = __shfl_xor(s1, 4);
;       if (b) { w.x = r0; w.y = r1; } else { w.z = r0; w.w = r1; } }
;     { const bool b = (lane & 2) != 0;
;       const unsigned s0 = b ? w.x : w.y, s1 = b ? w.z : w.w, r0 = __shfl_xor(s0, 2), r1 = __shfl_xor(s1, 2);
;       if (b) { w.x = r0; w.z = r1; } else { w.y = r0; w.w = r1; } }
;     { const bool b = (lane & 1) != 0;
;       const unsigned p0 = __shfl_xor(w.x, 1), p1 = __shfl_xor(w.y, 1), p2 = __shfl_xor(w.z, 1), p3 = __shfl_xor(w.w, 1);
;       if (b) { w.x = (p0 >> 16) | (w.x & 0xffff0000u); w.y = (p1 >> 16) | (w.y & 0xffff0000u); w.z = (p2 >> 16) | (w.z & 0xffff0000u); w.w = (p3 >> 16) | (w.w & 0xffff0000u); }
;       else   { w.x = (w.x & 0xffffu) | (p0 << 16); w.y = (w.y & 0xffffu) | (p1 << 16); w.z = (w.z & 0xffffu) | (p2 << 16); w.w = (w.w & 0xffffu) | (p3 << 16); } }
;     DI void operator()(const f32x4 (&acc)[2][2][4][2], const Unit& u, int wr, int wc, int fr, int fq) const {
;     ...
;                         bf16_t* t = vt + (((size_t)((row >> 6) * 4 + head) * 8 + ((row >> 3) & 7)) * 128 + f0 + (fr & 7)) * 8;
; #pragma unroll
;                         for (int bj = 0; bj < 2; ++bj) {
;                             const f32x4 x0 = acc[ai][bj][m][0], x1 = acc[ai][bj][m][1];
;                             u32x4 w; w.x = pk2(x0[0], x0[1]); w.y = pk2(x0[2], x0[3]); w.z = pk2(x1[0], x1[1]); w.w = pk2(x1[2], x1[3]);
;                             *(u32x4*)(t + 64 * bj * 8) = tr8x8(w, fr);
.LBB0_196:
	s_or_b64 exec, exec, s[10:11]
	global_store_dwordx4 v[134:135], v[128:131], off offset:1024
	s_nop 1
	v_cvt_pk_bf16_f32 v128, v28, v29
	v_cvt_pk_bf16_f32 v129, v30, v31
	v_cvt_pk_bf16_f32 v130, v24, v25
	v_cvt_pk_bf16_f32 v131, v26, v27
	v_cndmask_b32_e64 v134, v128, v130, s[8:9]
	v_cndmask_b32_e64 v135, v129, v131, s[8:9]
	s_nop 1
	v_mov_b32_dpp v134, v134 row_half_mirror row_mask:0xf bank_mask:0xf
	s_nop 1
	v_mov_b32_dpp v134, v134 quad_perm:[3,2,1,0] row_mask:0xf bank_mask:0xf
	s_nop 1
	v_mov_b32_dpp v135, v135 row_half_mirror row_mask:0xf bank_mask:0xf
	s_nop 1
	v_mov_b32_dpp v135, v135 quad_perm:[3,2,1,0] row_mask:0xf bank_mask:0xf
	s_waitcnt lgkmcnt(0)
	v_cndmask_b32_e64 v130, v130, v134, s[8:9]
	v_cndmask_b32_e64 v131, v131, v135, s[8:9]
	v_cndmask_b32_e64 v129, v135, v129, s[8:9]
	v_cndmask_b32_e64 v128, v134, v128, s[8:9]
	v_cndmask_b32_e64 v134, v128, v129, s[6:7]
	v_cndmask_b32_e64 v135, v130, v131, s[6:7]
	s_nop 1
	v_mov_b32_dpp v139, v134 quad_perm:[2,3,0,1] row_mask:0xf bank_mask:0xf
	s_nop 1
	v_mov_b32_dpp v135, v135 quad_perm:[2,3,0,1] row_mask:0xf bank_mask:0xf
	s_waitcnt lgkmcnt(0)
	v_cndmask_b32_e64 v138, v129, v139, s[6:7]
	v_cndmask_b32_e64 v134, v131, v135, s[6:7]
	v_cndmask_b32_e64 v135, v135, v130, s[6:7]
	v_cndmask_b32_e64 v142, v139, v128, s[6:7]
	s_nop 1
	v_mov_b32_dpp v160, v142 quad_perm:[1,0,3,2] row_mask:0xf bank_mask:0xf
	s_nop 1
	v_mov_b32_dpp v159, v138 quad_perm:[1,0,3,2] row_mask:0xf bank_mask:0xf
	s_nop 1
	v_mov_b32_dpp v143, v135 quad_perm:[1,0,3,2] row_mask:0xf bank_mask:0xf
	s_nop 1
	v_mov_b32_dpp v139, v134 quad_perm:[1,0,3,2] row_mask:0xf bank_mask:0xf
	s_and_saveexec_b64 s[10:11], vcc
	s_xor_b64 s[10:11], exec, s[10:11]
	s_cbranch_execz .LBB0_198
	s_waitcnt lgkmcnt(0)
	v_lshrrev_b32_e32 v128, 16, v160
	v_lshrrev_b32_e32 v129, 16, v159
	v_lshrrev_b32_e32 v130, 16, v143
	v_lshrrev_b32_e32 v131, 16, v139
	v_and_or_b32 v128, v142, s21, v128
	v_and_or_b32 v129, v138, s21, v129
	v_and_or_b32 v130, v135, s21, v130
	v_and_or_b32 v131, v134, s21, v131

; DI unsigned pk2(float lo, float hi) { f32x2 v = {lo, hi}; bf16x2_t b = __builtin_convertvector(v, bf16x2_t); return __builtin_bit_cast(unsigned, b); }
; DI u32x4 tr8x8(u32x4 w, int lane) {
;     { const bool b = (lane & 4) != 0;
;       const unsigned s0 = b ? w.x : w.z, s1 = b ? w.y : w.w, r0 = __shfl_xor(s0, 4), r1 = __shfl_xor(s1, 4);
;       if (b) { w.x = r0; w.y = r1; } else { w.z = r0; w.w = r1; } }
;     { const bool b = (lane & 2) != 0;
;       const unsigned s0 = b ? w.x : w.y, s1 = b ? w.z : w.w, r0 = __shfl_xor(s0, 2), r1 = __shfl_xor(s1, 2);
;       if (b) { w.x = r0; w.z = r1; } else { w.y = r0; w.w = r1; } }
;     { const bool b = (lane & 1) != 0;
;       const unsigned p0 = __shfl_xor(w.x, 1), p1 = __shfl_xor(w.y, 1), p2 = __shfl_xor(w.z, 1), p3 = __shfl_xor(w.w, 1);
;       if (b) { w.x = (p0 >> 16) | (w.x & 0xffff0000u); w.y = (p1 >> 16) | (w.y & 0xffff0000u); w.z = (p2 >> 16) | (w.z & 0xffff0000u); w.w = (p3 >> 16) | (w.w & 0xffff0000u); }
;       else   { w.x = (w.x & 0xffffu) | (p0 << 16); w.y = (w.y & 0xffffu) | (p1 << 16); w.z = (w.z & 0xffffu) | (p2 << 16); w.w = (w.w & 0xffffu) | (p3 << 16); } }
;     DI void operator()(const f32x4 (&acc)[2][2][4][2], const Unit& u, int wr, int wc, int fr, int fq) const {
;     ...
;                         bf16_t* t = vt + (((size_t)((row >> 6) * 4 + head) * 8 + ((row >> 3) & 7)) * 128 + f0 + (fr & 7)) * 8;
; #pragma unroll
;                         for (int bj = 0; bj < 2; ++bj) {
;                             const f32x4 x0 = acc[ai][bj][m][0], x1 = acc[ai][bj][m][1];
;                             u32x4 w; w.x = pk2(x0[0], x0[1]); w.y = pk2(x0[2], x0[3]); w.z = pk2(x1[0], x1[1]); w.w = pk2(x1[2], x1[3]);
;                             *(u32x4*)(t + 64 * bj * 8) = tr8x8(w, fr);
.LBB0_200:
	s_or_b64 exec, exec, s[10:11]
	v_add_u32_e32 v138, 0xa0, v158
	v_ashrrev_i32_e32 v134, 4, v138
	v_and_or_b32 v134, v134, -4, s19
	v_ashrrev_i32_e32 v135, 31, v134
	v_lshlrev_b32_e32 v138, 4, v138
	s_waitcnt lgkmcnt(0)
	v_and_b32_e32 v160, 0x380, v138
	v_lshlrev_b64 v[134:135], 14, v[134:135]
	v_lshl_add_u64 v[138:139], v[132:133], 0, v[160:161]
	v_lshl_add_u64 v[134:135], s[46:47], 0, v[134:135]
	v_lshl_add_u64 v[134:135], v[138:139], 4, v[134:135]
	global_store_dwordx4 v[134:135], v[128:131], off
	s_nop 1
	v_cvt_pk_bf16_f32 v128, v20, v21
	v_cvt_pk_bf16_f32 v129, v22, v23
	v_cvt_pk_bf16_f32 v130, v16, v17
	v_cvt_pk_bf16_f32 v131, v18, v19
	v_cndmask_b32_e64 v138, v128, v130, s[8:9]
	v_cndmask_b32_e64 v139, v129, v131, s[8:9]
	s_nop 1
	v_mov_b32_dpp v138, v138 row_half_mirror row_mask:0xf bank_mask:0xf
	s_nop 1
	v_mov_b32_dpp v138, v138 quad_perm:[3,2,1,0] row_mask:0xf bank_mask:0xf
	s_nop 1
	v_mov_b32_dpp v139, v139 row_half_mirror row_mask:0xf bank_mask:0xf
	s_nop 1
	v_mov_b32_dpp v139, v139 quad_perm:[3,2,1,0] row_mask:0xf bank_mask:0xf
	s_waitcnt lgkmcnt(0)
	v_cndmask_b32_e64 v130, v130, v138, s[8:9]
	v_cndmask_b32_e64 v131, v131, v139, s[8:9]
	v_cndmask_b32_e64 v129, v139, v129, s[8:9]
	v_cndmask_b32_e64 v128, v138, v128, s[8:9]
	v_cndmask_b32_e64 v138, v128, v129, s[6:7]
	v_cndmask_b32_e64 v139, v130, v131, s[6:7]
	s_nop 1
	v_mov_b32_dpp v143, v138 quad_perm:[2,3,0,1] row_mask:0xf bank_mask:0xf
	s_nop 1
	v_mov_b32_dpp v139, v139 quad_perm:[2,3,0,1] row_mask:0xf bank_mask:0xf
	s_waitcnt lgkmcnt(0)
	v_cndmask_b32_e64 v142, v129, v143, s[6:7]
	v_cndmask_b32_e64 v138, v131, v139, s[6:7]
	v_cndmask_b32_e64 v139, v139, v130, s[6:7]
	v_cndmask_b32_e64 v159, v143, v128, s[6:7]
	s_nop 1
	v_mov_b32_dpp v176, v159 quad_perm:[1,0,3,2] row_mask:0xf bank_mask:0xf
	s_nop 1
	v_mov_b32_dpp v175, v142 quad_perm:[1,0,3,2] row_mask:0xf bank_mask:0xf
	s_nop 1
	v_mov_b32_dpp v160, v139 quad_perm:[1,0,3,2] row_mask:0xf bank_mask:0xf
	s_nop 1
	v_mov_b32_dpp v143, v138 quad_perm:[1,0,3,2] row_mask:0xf bank_mask:0xf
	s_and_saveexec_b64 s[10:11], vcc
	s_xor_b64 s[10:11], exec, s[10:11]
	s_cbranch_execz .LBB0_202
	s_waitcnt lgkmcnt(0)
	v_lshrrev_b32_e32 v128, 16, v176
	v_lshrrev_b32_e32 v129, 16, v175
	v_lshrrev_b32_e32 v130, 16, v160
	v_lshrrev_b32_e32 v131, 16, v143
	v_and_or_b32 v128, v159, s21, v128
	v_and_or_b32 v129, v142, s21, v129
	v_and_or_b32 v130, v139, s21, v130
	v_and_or_b32 v131, v138, s21, v131

; DI unsigned pk2(float lo, float hi) { f32x2 v = {lo, hi}; bf16x2_t b = __builtin_convertvector(v, bf16x2_t); return __builtin_bit_cast(unsigned, b); }
; DI u32x4 tr8x8(u32x4 w, int lane) {
;     { const bool b = (lane & 4) != 0;
;       const unsigned s0 = b ? w.x : w.z, s1 = b ? w.y : w.w, r0 = __shfl_xor(s0, 4), r1 = __shfl_xor(s1, 4);
;       if (b) { w.x = r0; w.y = r1; } else { w.z = r0; w.w = r1; } }
;     { const bool b = (lane & 2) != 0;
;       const unsigned s0 = b ? w.x : w.y, s1 = b ? w.z : w.w, r0 = __shfl_xor(s0, 2), r1 = __shfl_xor(s1, 2);
;       if (b) { w.x = r0; w.z = r1; } else { w.y = r0; w.w = r1; } }
;     { const bool b = (lane & 1) != 0;
;       const unsigned p0 = __shfl_xor(w.x, 1), p1 = __shfl_xor(w.y, 1), p2 = __shfl_xor(w.z, 1), p3 = __shfl_xor(w.w, 1);
;       if (b) { w.x = (p0 >> 16) | (w.x & 0xffff0000u); w.y = (p1 >> 16) | (w.y & 0xffff0000u); w.z = (p2 >> 16) | (w.z & 0xffff0000u); w.w = (p3 >> 16) | (w.w & 0xffff0000u); }
;       else   { w.x = (w.x & 0xffffu) | (p0 << 16); w.y = (w.y & 0xffffu) | (p1 << 16); w.z = (w.z & 0xffffu) | (p2 << 16); w.w = (w.w & 0xffffu) | (p3 << 16); } }
;     DI void operator()(const f32x4 (&acc)[2][2][4][2], const Unit& u, int wr, int wc, int fr, int fq) const {
;     ...
;                         bf16_t* t = vt + (((size_t)((row >> 6) * 4 + head) * 8 + ((row >> 3) & 7)) * 128 + f0 + (fr & 7)) * 8;
; #pragma unroll
;                         for (int bj = 0; bj < 2; ++bj) {
;                             const f32x4 x0 = acc[ai][bj][m][0], x1 = acc[ai][bj][m][1];
;                             u32x4 w; w.x = pk2(x0[0], x0[1]); w.y = pk2(x0[2], x0[3]); w.z = pk2(x1[0], x1[1]); w.w = pk2(x1[2], x1[3]);
;                             *(u32x4*)(t + 64 * bj * 8) = tr8x8(w, fr);
.LBB0_204:
	s_or_b64 exec, exec, s[10:11]
	global_store_dwordx4 v[134:135], v[128:131], off offset:1024
	s_nop 1
	v_cvt_pk_bf16_f32 v128, v12, v13
	v_cvt_pk_bf16_f32 v129, v14, v15
	v_cvt_pk_bf16_f32 v130, v8, v9
	v_cvt_pk_bf16_f32 v131, v10, v11
	v_cndmask_b32_e64 v134, v128, v130, s[8:9]
	v_cndmask_b32_e64 v135, v129, v131, s[8:9]
	s_nop 1
	v_mov_b32_dpp v134, v134 row_half_mirror row_mask:0xf bank_mask:0xf
	s_nop 1
	v_mov_b32_dpp v134, v134 quad_perm:[3,2,1,0] row_mask:0xf bank_mask:0xf
	s_nop 1
	v_mov_b32_dpp v135, v135 row_half_mirror row_mask:0xf bank_mask:0xf
	s_nop 1
	v_mov_b32_dpp v135, v135 quad_perm:[3,2,1,0] row_mask:0xf bank_mask:0xf
	s_waitcnt lgkmcnt(0)
	v_cndmask_b32_e64 v130, v130, v134, s[8:9]
	v_cndmask_b32_e64 v131, v131, v135, s[8:9]
	v_cndmask_b32_e64 v129, v135, v129, s[8:9]
	v_cndmask_b32_e64 v128, v134, v128, s[8:9]
	v_cndmask_b32_e64 v134, v128, v129, s[6:7]
	v_cndmask_b32_e64 v135, v130, v131, s[6:7]
	s_nop 1
	v_mov_b32_dpp v139, v134 quad_perm:[2,3,0,1] row_mask:0xf bank_mask:0xf
	s_nop 1
	v_mov_b32_dpp v135, v135 quad_perm:[2,3,0,1] row_mask:0xf bank_mask:0xf
	s_waitcnt lgkmcnt(0)
	v_cndmask_b32_e64 v138, v129, v139, s[6:7]
	v_cndmask_b32_e64 v134, v131, v135, s[6:7]
	v_cndmask_b32_e64 v135, v135, v130, s[6:7]
	v_cndmask_b32_e64 v142, v139, v128, s[6:7]
	s_nop 1
	v_mov_b32_dpp v160, v142 quad_perm:[1,0,3,2] row_mask:0xf bank_mask:0xf
	s_nop 1
	v_mov_b32_dpp v159, v138 quad_perm:[1,0,3,2] row_mask:0xf bank_mask:0xf
	s_nop 1
	v_mov_b32_dpp v143, v135 quad_perm:[1,0,3,2] row_mask:0xf bank_mask:0xf
	s_nop 1
	v_mov_b32_dpp v139, v134 quad_perm:[1,0,3,2] row_mask:0xf bank_mask:0xf
	s_and_saveexec_b64 s[10:11], vcc
	s_xor_b64 s[10:11], exec, s[10:11]
	s_cbranch_execz .LBB0_206
	s_waitcnt lgkmcnt(0)
	v_lshrrev_b32_e32 v128, 16, v160
	v_lshrrev_b32_e32 v129, 16, v159
	v_lshrrev_b32_e32 v130, 16, v143
	v_lshrrev_b32_e32 v131, 16, v139
	v_and_or_b32 v128, v142, s21, v128
	v_and_or_b32 v129, v138, s21, v129
	v_and_or_b32 v130, v135, s21, v130
	v_and_or_b32 v131, v134, s21, v131

; DI unsigned pk2(float lo, float hi) { f32x2 v = {lo, hi}; bf16x2_t b = __builtin_convertvector(v, bf16x2_t); return __builtin_bit_cast(unsigned, b); }
; DI u32x4 tr8x8(u32x4 w, int lane) {
;     { const bool b = (lane & 4) != 0;
;       const unsigned s0 = b ? w.x : w.z, s1 = b ? w.y : w.w, r0 = __shfl_xor(s0, 4), r1 = __shfl_xor(s1, 4);
;       if (b) { w.x = r0; w.y = r1; } else { w.z = r0; w.w = r1; } }
;     { const bool b = (lane & 2) != 0;
;       const unsigned s0 = b ? w.x : w.y, s1 = b ? w.z : w.w, r0 = __shfl_xor(s0, 2), r1 = __shfl_xor(s1, 2);
;       if (b) { w.x = r0; w.z = r1; } else { w.y = r0; w.w = r1; } }
;     { const bool b = (lane & 1) != 0;
;       const unsigned p0 = __shfl_xor(w.x, 1), p1 = __shfl_xor(w.y, 1), p2 = __shfl_xor(w.z, 1), p3 = __shfl_xor(w.w, 1);
;       if (b) { w.x = (p0 >> 16) | (w.x & 0xffff0000u); w.y = (p1 >> 16) | (w.y & 0xffff0000u); w.z = (p2 >> 16) | (w.z & 0xffff0000u); w.w = (p3 >> 16) | (w.w & 0xffff0000u); }
;       else   { w.x = (w.x & 0xffffu) | (p0 << 16); w.y = (w.y & 0xffffu) | (p1 << 16); w.z = (w.z & 0xffffu) | (p2 << 16); w.w = (w.w & 0xffffu) | (p3 << 16); } }
;     DI void operator()(const f32x4 (&acc)[2][2][4][2], const Unit& u, int wr, int wc, int fr, int fq) const {
;     ...
;                         bf16_t* t = vt + (((size_t)((row >> 6) * 4 + head) * 8 + ((row >> 3) & 7)) * 128 + f0 + (fr & 7)) * 8;
; #pragma unroll
;                         for (int bj = 0; bj < 2; ++bj) {
;                             const f32x4 x0 = acc[ai][bj][m][0], x1 = acc[ai][bj][m][1];
;                             u32x4 w; w.x = pk2(x0[0], x0[1]); w.y = pk2(x0[2], x0[3]); w.z = pk2(x1[0], x1[1]); w.w = pk2(x1[2], x1[3]);
;                             *(u32x4*)(t + 64 * bj * 8) = tr8x8(w, fr);
.LBB0_208:
	s_or_b64 exec, exec, s[10:11]
	v_add_u32_e32 v138, 0xb0, v158
	v_ashrrev_i32_e32 v134, 4, v138
	v_and_or_b32 v134, v134, -4, s19
	v_ashrrev_i32_e32 v135, 31, v134
	v_lshlrev_b32_e32 v138, 4, v138
	s_waitcnt lgkmcnt(0)
	v_and_b32_e32 v160, 0x380, v138
	v_lshlrev_b64 v[134:135], 14, v[134:135]
	v_lshl_add_u64 v[132:133], v[132:133], 0, v[160:161]
	v_lshl_add_u64 v[134:135], s[46:47], 0, v[134:135]
	v_lshl_add_u64 v[132:133], v[132:133], 4, v[134:135]
	global_store_dwordx4 v[132:133], v[128:131], off
	s_nop 1
	v_cvt_pk_bf16_f32 v128, v4, v5
	v_cvt_pk_bf16_f32 v129, v6, v7
	v_cvt_pk_bf16_f32 v130, v0, v1
	v_cvt_pk_bf16_f32 v131, v2, v3
	v_cndmask_b32_e64 v134, v128, v130, s[8:9]
	v_cndmask_b32_e64 v135, v129, v131, s[8:9]
	s_nop 1
	v_mov_b32_dpp v134, v134 row_half_mirror row_mask:0xf bank_mask:0xf
	s_nop 1
	v_mov_b32_dpp v134, v134 quad_perm:[3,2,1,0] row_mask:0xf bank_mask:0xf
	s_nop 1
	v_mov_b32_dpp v135, v135 row_half_mirror row_mask:0xf bank_mask:0xf
	s_nop 1
	v_mov_b32_dpp v135, v135 quad_perm:[3,2,1,0] row_mask:0xf bank_mask:0xf
	s_waitcnt lgkmcnt(0)
	v_cndmask_b32_e64 v130, v130, v134, s[8:9]
	v_cndmask_b32_e64 v131, v131, v135, s[8:9]
	v_cndmask_b32_e64 v129, v135, v129, s[8:9]
	v_cndmask_b32_e64 v128, v134, v128, s[8:9]
	v_cndmask_b32_e64 v134, v128, v129, s[6:7]
	v_cndmask_b32_e64 v135, v130, v131, s[6:7]
	s_nop 1
	v_mov_b32_dpp v139, v134 quad_perm:[2,3,0,1] row_mask:0xf bank_mask:0xf
	s_nop 1
	v_mov_b32_dpp v135, v135 quad_perm:[2,3,0,1] row_mask:0xf bank_mask:0xf
	s_waitcnt lgkmcnt(0)
	v_cndmask_b32_e64 v138, v129, v139, s[6:7]
	v_cndmask_b32_e64 v134, v131, v135, s[6:7]
	v_cndmask_b32_e64 v135, v135, v130, s[6:7]
	v_cndmask_b32_e64 v139, v139, v128, s[6:7]
	s_nop 1
	v_mov_b32_dpp v142, v139 quad_perm:[1,0,3,2] row_mask:0xf bank_mask:0xf
	s_nop 1
	v_mov_b32_dpp v141, v138 quad_perm:[1,0,3,2] row_mask:0xf bank_mask:0xf
	s_nop 1
	v_mov_b32_dpp v140, v135 quad_perm:[1,0,3,2] row_mask:0xf bank_mask:0xf
	s_nop 1
	v_mov_b32_dpp v137, v134 quad_perm:[1,0,3,2] row_mask:0xf bank_mask:0xf
	s_and_saveexec_b64 s[6:7], vcc
	s_xor_b64 s[6:7], exec, s[6:7]
	s_cbranch_execz .LBB0_210
	s_waitcnt lgkmcnt(0)
	v_lshrrev_b32_e32 v128, 16, v142
	v_lshrrev_b32_e32 v129, 16, v141
	v_lshrrev_b32_e32 v130, 16, v140
	v_lshrrev_b32_e32 v131, 16, v137
	v_and_or_b32 v128, v139, s21, v128
	v_and_or_b32 v129, v138, s21, v129
	v_and_or_b32 v130, v135, s21, v130
	v_and_or_b32 v131, v134, s21, v131
